# barrier spin loops poll every 512 clocks instead of 64 (fewer hot-spot polls while stragglers finish)
# baseline (speedup 1.0000x reference)
; #define LAS __attribute__((address_space(3)))
; __global__ void __launch_bounds__(512, 2) hymba_fwd(Params p) {
;     ...
;     cg::grid_group grid = cg::this_grid();
;     const int G = gridDim.x, bx = blockIdx.x;
;     const int vcu = (G % 8 == 0) ? (bx % 8) * (G / 8) + bx / 8 : bx;
;     unsigned char* ws = p.ws;
;     float* ssf = (float*)(ws + WS_SS);
;     const int lo = p.ph_lo, hi = p.ph_hi;
;     volatile LAS unsigned* bst = (volatile LAS unsigned*)(lds + LDS_BYTES - 16);
;     if (threadIdx.x < 4) bst[threadIdx.x] = 0u;
;     __syncthreads();
;     XcdBarrier xbar = xcd_barrier_post((unsigned*)(ws + WS_BAR) + p.li * XCD_BAR_WORDS, bst);
;     if (lo == 12345) grid.sync();
.LBB0_16:
	s_sleep 8
	global_load_dword v2, v0, s[2:3] offset:32 sc1
	s_waitcnt vmcnt(0)
	v_and_b32_e32 v2, 0xffff0000, v2
	v_cmp_ne_u32_e32 vcc, v2, v1
	s_or_b64 s[8:9], vcc, s[8:9]
	s_andn2_b64 exec, exec, s[8:9]
	s_cbranch_execnz .LBB0_16

; __device__ __forceinline__ unsigned xb_ld(unsigned* p)              { return __hip_atomic_load(p, __ATOMIC_RELAXED, __HIP_MEMORY_SCOPE_AGENT); }
; __device__ __forceinline__ void xcd_barrier_complete(unsigned* bar, unsigned x, unsigned& nloc, unsigned& nx) {
;     const unsigned G = gridDim.x * gridDim.y * gridDim.z;
;     unsigned sum, cnt, mine, sp = 0u;
;     for (;;) {
;         sum = 0u; cnt = 0u; mine = 0u;
; #pragma unroll
;         for (unsigned j = 0; j < 16; ++j) { const unsigned c = xb_ld(&bar[XB_XCNT(j)]); sum += c; cnt += (c > 0u) ? 1u : 0u; mine = (j == x) ? c : mine; }
;         if (sum == G) break;
;         __builtin_amdgcn_s_sleep(1);
;         if ((++sp & 255u) == 0u) { if (xb_ld(&bar[XB_TMO])) break; if (sp > XB_SPIN_CAP) { atomicAdd(&bar[XB_TMO], 1u); break; } }
;     }
.LBB0_87:
	global_load_dword v15, v16, s[26:27] offset:1024 sc1
	global_load_dword v0, v16, s[26:27] offset:1280 sc1
	global_load_dword v1, v16, s[26:27] offset:1536 sc1
	global_load_dword v2, v16, s[26:27] offset:1792 sc1
	global_load_dword v3, v16, s[26:27] offset:2048 sc1
	global_load_dword v4, v16, s[26:27] offset:2304 sc1
	global_load_dword v5, v16, s[26:27] offset:2560 sc1
	global_load_dword v6, v16, s[26:27] offset:2816 sc1
	global_load_dword v7, v16, s[26:27] offset:3072 sc1
	global_load_dword v8, v16, s[26:27] offset:3328 sc1
	global_load_dword v9, v16, s[26:27] offset:3584 sc1
	global_load_dword v10, v16, s[26:27] offset:3840 sc1
	global_load_dword v11, v16, s[8:9] sc1
	global_load_dword v12, v16, s[10:11] sc1
	global_load_dword v13, v16, s[12:13] sc1
	global_load_dword v14, v16, s[14:15] sc1
	s_mov_b64 s[16:17], -1
	s_mov_b64 s[30:31], -1
	s_waitcnt vmcnt(14)
	v_add_u32_e32 v17, v0, v15
	s_waitcnt vmcnt(13)
	v_add_u32_e32 v17, v17, v1
	s_waitcnt vmcnt(12)
	v_add_u32_e32 v17, v17, v2
	s_waitcnt vmcnt(11)
	v_add_u32_e32 v17, v17, v3
	s_waitcnt vmcnt(10)
	v_add_u32_e32 v17, v17, v4
	s_waitcnt vmcnt(9)
	v_add_u32_e32 v17, v17, v5
	s_waitcnt vmcnt(8)
	v_add_u32_e32 v17, v17, v6
	s_waitcnt vmcnt(7)
	v_add_u32_e32 v17, v17, v7
	s_waitcnt vmcnt(6)
	v_add_u32_e32 v17, v17, v8
	s_waitcnt vmcnt(5)
	v_add_u32_e32 v17, v17, v9
	s_waitcnt vmcnt(4)
	v_add_u32_e32 v17, v17, v10
	s_waitcnt vmcnt(3)
	v_add_u32_e32 v17, v17, v11
	s_waitcnt vmcnt(2)
	v_add_u32_e32 v17, v17, v12
	s_waitcnt vmcnt(1)
	v_add_u32_e32 v17, v17, v13
	s_waitcnt vmcnt(0)
	v_add_u32_e32 v17, v17, v14
	v_cmp_eq_u32_e32 vcc, s6, v17
	s_cbranch_vccnz .LBB0_86
	s_and_b32 s16, s7, 0xff
	s_cmp_eq_u32 s16, 0
	s_mov_b64 s[16:17], -1
	s_mov_b64 s[34:35], -1
	s_sleep 8
	s_cbranch_scc0 .LBB0_91
	global_load_dword v17, v16, s[26:27] offset:512 sc1
	s_waitcnt vmcnt(0)
	v_cmp_eq_u32_e32 vcc, 0, v17
	s_cbranch_vccnz .LBB0_93
	s_mov_b64 s[34:35], 0

; __device__ __forceinline__ unsigned xb_ld(unsigned* p)              { return __hip_atomic_load(p, __ATOMIC_RELAXED, __HIP_MEMORY_SCOPE_AGENT); }
; #define XB_SPIN(cond, bar) do { unsigned _sp = 0; while (cond) { __builtin_amdgcn_s_sleep(1); \
;     if ((++_sp & 255u) == 0u) { if (xb_ld(&(bar)[XB_TMO])) break; if (_sp > XB_SPIN_CAP) { atomicAdd(&(bar)[XB_TMO], 1u); break; } } } } while (0)
; __device__ __forceinline__ void xcd_barrier(const XcdBarrier& b) {
;     ...
;             XB_SPIN(xb_ld(&bar[XB_XGEN(b.x)]) == gen, bar);
.LBB0_105:
	s_and_b32 s7, s6, 0xff
	s_mov_b64 s[34:35], -1
	s_cmp_lg_u32 s7, 0
	s_mov_b64 s[60:61], -1
	s_sleep 8
	s_cbranch_scc1 .LBB0_108
	global_load_dword v2, v0, s[26:27] offset:512 sc1
	s_waitcnt vmcnt(0)
	v_cmp_eq_u32_e32 vcc, 0, v2
	s_cbranch_vccnz .LBB0_110
	s_mov_b64 s[60:61], 0
	s_mov_b64 s[38:39], -1

; __device__ __forceinline__ unsigned xb_ld(unsigned* p)              { return __hip_atomic_load(p, __ATOMIC_RELAXED, __HIP_MEMORY_SCOPE_AGENT); }
; #define XB_SPIN(cond, bar) do { unsigned _sp = 0; while (cond) { __builtin_amdgcn_s_sleep(1); \
;     if ((++_sp & 255u) == 0u) { if (xb_ld(&(bar)[XB_TMO])) break; if (_sp > XB_SPIN_CAP) { atomicAdd(&(bar)[XB_TMO], 1u); break; } } } } while (0)
; __device__ __forceinline__ void xcd_barrier(const XcdBarrier& b) {
;     ...
;             else XB_SPIN(xb_ld(&bar[XB_TOPGEN]) == tg, bar);
.LBB0_122:
	s_and_b32 s7, s6, 0xff
	s_cmp_lg_u32 s7, 0
	s_mov_b64 s[60:61], -1
	s_sleep 8
	s_cbranch_scc1 .LBB0_125
	global_load_dword v1, v0, s[14:15] sc1
	s_waitcnt vmcnt(0)
	v_cmp_eq_u32_e32 vcc, 0, v1
	s_cbranch_vccnz .LBB0_127
	s_mov_b64 s[60:61], 0
	s_mov_b64 s[38:39], -1

; __device__ __forceinline__ unsigned xb_ld(unsigned* p)              { return __hip_atomic_load(p, __ATOMIC_RELAXED, __HIP_MEMORY_SCOPE_AGENT); }
; __device__ __forceinline__ void xcd_barrier_complete(unsigned* bar, unsigned x, unsigned& nloc, unsigned& nx) {
;     const unsigned G = gridDim.x * gridDim.y * gridDim.z;
;     unsigned sum, cnt, mine, sp = 0u;
;     for (;;) {
;         sum = 0u; cnt = 0u; mine = 0u;
; #pragma unroll
;         for (unsigned j = 0; j < 16; ++j) { const unsigned c = xb_ld(&bar[XB_XCNT(j)]); sum += c; cnt += (c > 0u) ? 1u : 0u; mine = (j == x) ? c : mine; }
;         if (sum == G) break;
;         __builtin_amdgcn_s_sleep(1);
;         if ((++sp & 255u) == 0u) { if (xb_ld(&bar[XB_TMO])) break; if (sp > XB_SPIN_CAP) { atomicAdd(&bar[XB_TMO], 1u); break; } }
;     }
.LBB0_443:
	global_load_dword v15, v16, s[26:27] offset:1024 sc1
	s_waitcnt lgkmcnt(0)
	global_load_dword v0, v16, s[26:27] offset:1280 sc1
	global_load_dword v1, v16, s[26:27] offset:1536 sc1
	global_load_dword v2, v16, s[26:27] offset:1792 sc1
	global_load_dword v3, v16, s[26:27] offset:2048 sc1
	global_load_dword v4, v16, s[26:27] offset:2304 sc1
	global_load_dword v5, v16, s[26:27] offset:2560 sc1
	global_load_dword v6, v16, s[26:27] offset:2816 sc1
	global_load_dword v7, v16, s[26:27] offset:3072 sc1
	global_load_dword v8, v16, s[26:27] offset:3328 sc1
	global_load_dword v9, v16, s[26:27] offset:3584 sc1
	global_load_dword v10, v16, s[26:27] offset:3840 sc1
	global_load_dword v11, v16, s[4:5] sc1
	global_load_dword v12, v16, s[8:9] sc1
	global_load_dword v13, v16, s[10:11] sc1
	global_load_dword v14, v16, s[12:13] sc1
	s_mov_b64 s[14:15], -1
	s_mov_b64 s[16:17], -1
	s_waitcnt vmcnt(14)
	v_add_u32_e32 v17, v0, v15
	s_waitcnt vmcnt(13)
	v_add_u32_e32 v17, v17, v1
	s_waitcnt vmcnt(12)
	v_add_u32_e32 v17, v17, v2
	s_waitcnt vmcnt(11)
	v_add_u32_e32 v17, v17, v3
	s_waitcnt vmcnt(10)
	v_add_u32_e32 v17, v17, v4
	s_waitcnt vmcnt(9)
	v_add_u32_e32 v17, v17, v5
	s_waitcnt vmcnt(8)
	v_add_u32_e32 v17, v17, v6
	s_waitcnt vmcnt(7)
	v_add_u32_e32 v17, v17, v7
	s_waitcnt vmcnt(6)
	v_add_u32_e32 v17, v17, v8
	s_waitcnt vmcnt(5)
	v_add_u32_e32 v17, v17, v9
	s_waitcnt vmcnt(4)
	v_add_u32_e32 v17, v17, v10
	s_waitcnt vmcnt(3)
	v_add_u32_e32 v17, v17, v11
	s_waitcnt vmcnt(2)
	v_add_u32_e32 v17, v17, v12
	s_waitcnt vmcnt(1)
	v_add_u32_e32 v17, v17, v13
	s_waitcnt vmcnt(0)
	v_add_u32_e32 v17, v17, v14
	v_cmp_eq_u32_e32 vcc, s6, v17
	s_cbranch_vccnz .LBB0_442
	s_and_b32 s14, s7, 0xff
	s_cmp_eq_u32 s14, 0
	s_mov_b64 s[14:15], -1
	s_mov_b64 s[30:31], -1
	s_sleep 8
	s_cbranch_scc0 .LBB0_447
	global_load_dword v17, v16, s[26:27] offset:512 sc1
	s_waitcnt vmcnt(0)
	v_cmp_eq_u32_e32 vcc, 0, v17
	s_cbranch_vccnz .LBB0_449
	s_mov_b64 s[30:31], 0

; __device__ __forceinline__ unsigned xb_ld(unsigned* p)              { return __hip_atomic_load(p, __ATOMIC_RELAXED, __HIP_MEMORY_SCOPE_AGENT); }
; #define XB_SPIN(cond, bar) do { unsigned _sp = 0; while (cond) { __builtin_amdgcn_s_sleep(1); \
;     if ((++_sp & 255u) == 0u) { if (xb_ld(&(bar)[XB_TMO])) break; if (_sp > XB_SPIN_CAP) { atomicAdd(&(bar)[XB_TMO], 1u); break; } } } } while (0)
; __device__ __forceinline__ void xcd_barrier(const XcdBarrier& b) {
;     ...
;             XB_SPIN(xb_ld(&bar[XB_XGEN(b.x)]) == gen, bar);
.LBB0_461:
	s_and_b32 s7, s6, 0xff
	s_mov_b64 s[30:31], -1
	s_cmp_lg_u32 s7, 0
	s_mov_b64 s[38:39], -1
	s_sleep 8
	s_cbranch_scc1 .LBB0_464
	global_load_dword v2, v0, s[26:27] offset:512 sc1
	s_waitcnt vmcnt(0)
	v_cmp_eq_u32_e32 vcc, 0, v2
	s_cbranch_vccnz .LBB0_466
	s_mov_b64 s[38:39], 0
	s_mov_b64 s[34:35], -1

; __device__ __forceinline__ unsigned xb_ld(unsigned* p)              { return __hip_atomic_load(p, __ATOMIC_RELAXED, __HIP_MEMORY_SCOPE_AGENT); }
; #define XB_SPIN(cond, bar) do { unsigned _sp = 0; while (cond) { __builtin_amdgcn_s_sleep(1); \
;     if ((++_sp & 255u) == 0u) { if (xb_ld(&(bar)[XB_TMO])) break; if (_sp > XB_SPIN_CAP) { atomicAdd(&(bar)[XB_TMO], 1u); break; } } } } while (0)
; __device__ __forceinline__ void xcd_barrier(const XcdBarrier& b) {
;     ...
;             else XB_SPIN(xb_ld(&bar[XB_TOPGEN]) == tg, bar);
.LBB0_478:
	s_and_b32 s7, s6, 0xff
	s_cmp_lg_u32 s7, 0
	s_mov_b64 s[38:39], -1
	s_sleep 8
	s_cbranch_scc1 .LBB0_481
	global_load_dword v1, v0, s[12:13] sc1
	s_waitcnt vmcnt(0)
	v_cmp_eq_u32_e32 vcc, 0, v1
	s_cbranch_vccnz .LBB0_483
	s_mov_b64 s[38:39], 0
	s_mov_b64 s[34:35], -1

; __device__ __forceinline__ unsigned xb_ld(unsigned* p)              { return __hip_atomic_load(p, __ATOMIC_RELAXED, __HIP_MEMORY_SCOPE_AGENT); }
; #define XB_SPIN(cond, bar) do { unsigned _sp = 0; while (cond) { __builtin_amdgcn_s_sleep(1); \
;     if ((++_sp & 255u) == 0u) { if (xb_ld(&(bar)[XB_TMO])) break; if (_sp > XB_SPIN_CAP) { atomicAdd(&(bar)[XB_TMO], 1u); break; } } } } while (0)
; __device__ __forceinline__ void xcd_barrier(const XcdBarrier& b) {
;     ...
;             XB_SPIN(xb_ld(&bar[XB_XGEN(b.x)]) == gen, bar);
.LBB0_899:
	s_and_b32 s7, s6, 0xff
	s_mov_b64 s[30:31], -1
	s_cmp_lg_u32 s7, 0
	s_mov_b64 s[36:37], -1
	s_sleep 8
	s_cbranch_scc1 .LBB0_902
	global_load_dword v2, v0, s[26:27] offset:512 sc1
	s_waitcnt vmcnt(0)
	v_cmp_eq_u32_e32 vcc, 0, v2
	s_cbranch_vccnz .LBB0_904
	s_mov_b64 s[36:37], 0
	s_mov_b64 s[34:35], -1

; __device__ __forceinline__ unsigned xb_ld(unsigned* p)              { return __hip_atomic_load(p, __ATOMIC_RELAXED, __HIP_MEMORY_SCOPE_AGENT); }
; #define XB_SPIN(cond, bar) do { unsigned _sp = 0; while (cond) { __builtin_amdgcn_s_sleep(1); \
;     if ((++_sp & 255u) == 0u) { if (xb_ld(&(bar)[XB_TMO])) break; if (_sp > XB_SPIN_CAP) { atomicAdd(&(bar)[XB_TMO], 1u); break; } } } } while (0)
; __device__ __forceinline__ void xcd_barrier(const XcdBarrier& b) {
;     ...
;             else XB_SPIN(xb_ld(&bar[XB_TOPGEN]) == tg, bar);
.LBB0_916:
	s_and_b32 s7, s6, 0xff
	s_cmp_lg_u32 s7, 0
	s_mov_b64 s[36:37], -1
	s_sleep 8
	s_cbranch_scc1 .LBB0_919
	global_load_dword v1, v0, s[12:13] sc1
	s_waitcnt vmcnt(0)
	v_cmp_eq_u32_e32 vcc, 0, v1
	s_cbranch_vccnz .LBB0_921
	s_mov_b64 s[36:37], 0
	s_mov_b64 s[34:35], -1

; __device__ __forceinline__ unsigned xb_ld(unsigned* p)              { return __hip_atomic_load(p, __ATOMIC_RELAXED, __HIP_MEMORY_SCOPE_AGENT); }
; __device__ __forceinline__ void xcd_barrier_complete(unsigned* bar, unsigned x, unsigned& nloc, unsigned& nx) {
;     const unsigned G = gridDim.x * gridDim.y * gridDim.z;
;     unsigned sum, cnt, mine, sp = 0u;
;     for (;;) {
;         sum = 0u; cnt = 0u; mine = 0u;
; #pragma unroll
;         for (unsigned j = 0; j < 16; ++j) { const unsigned c = xb_ld(&bar[XB_XCNT(j)]); sum += c; cnt += (c > 0u) ? 1u : 0u; mine = (j == x) ? c : mine; }
;         if (sum == G) break;
;         __builtin_amdgcn_s_sleep(1);
;         if ((++sp & 255u) == 0u) { if (xb_ld(&bar[XB_TMO])) break; if (sp > XB_SPIN_CAP) { atomicAdd(&bar[XB_TMO], 1u); break; } }
;     }
.LBB0_954:
	global_load_dword v15, v16, s[26:27] offset:1024 sc1
	s_waitcnt lgkmcnt(0)
	global_load_dword v0, v16, s[26:27] offset:1280 sc1
	global_load_dword v1, v16, s[26:27] offset:1536 sc1
	global_load_dword v2, v16, s[26:27] offset:1792 sc1
	global_load_dword v3, v16, s[26:27] offset:2048 sc1
	global_load_dword v4, v16, s[26:27] offset:2304 sc1
	global_load_dword v5, v16, s[26:27] offset:2560 sc1
	global_load_dword v6, v16, s[26:27] offset:2816 sc1
	global_load_dword v7, v16, s[26:27] offset:3072 sc1
	global_load_dword v8, v16, s[26:27] offset:3328 sc1
	global_load_dword v9, v16, s[26:27] offset:3584 sc1
	global_load_dword v10, v16, s[26:27] offset:3840 sc1
	global_load_dword v11, v16, s[4:5] sc1
	global_load_dword v12, v16, s[6:7] sc1
	global_load_dword v13, v16, s[8:9] sc1
	global_load_dword v14, v16, s[10:11] sc1
	s_mov_b64 s[12:13], -1
	s_mov_b64 s[14:15], -1
	s_waitcnt vmcnt(14)
	v_add_u32_e32 v17, v0, v15
	s_waitcnt vmcnt(13)
	v_add_u32_e32 v17, v17, v1
	s_waitcnt vmcnt(12)
	v_add_u32_e32 v17, v17, v2
	s_waitcnt vmcnt(11)
	v_add_u32_e32 v17, v17, v3
	s_waitcnt vmcnt(10)
	v_add_u32_e32 v17, v17, v4
	s_waitcnt vmcnt(9)
	v_add_u32_e32 v17, v17, v5
	s_waitcnt vmcnt(8)
	v_add_u32_e32 v17, v17, v6
	s_waitcnt vmcnt(7)
	v_add_u32_e32 v17, v17, v7
	s_waitcnt vmcnt(6)
	v_add_u32_e32 v17, v17, v8
	s_waitcnt vmcnt(5)
	v_add_u32_e32 v17, v17, v9
	s_waitcnt vmcnt(4)
	v_add_u32_e32 v17, v17, v10
	s_waitcnt vmcnt(3)
	v_add_u32_e32 v17, v17, v11
	s_waitcnt vmcnt(2)
	v_add_u32_e32 v17, v17, v12
	s_waitcnt vmcnt(1)
	v_add_u32_e32 v17, v17, v13
	s_waitcnt vmcnt(0)
	v_add_u32_e32 v17, v17, v14
	v_cmp_eq_u32_e32 vcc, s19, v17
	s_cbranch_vccnz .LBB0_953
	s_and_b32 s12, s25, 0xff
	s_cmp_eq_u32 s12, 0
	s_mov_b64 s[12:13], -1
	s_mov_b64 s[16:17], -1
	s_sleep 8
	s_cbranch_scc0 .LBB0_958
	global_load_dword v17, v16, s[26:27] offset:512 sc1
	s_waitcnt vmcnt(0)
	v_cmp_eq_u32_e32 vcc, 0, v17
	s_cbranch_vccnz .LBB0_960
	s_mov_b64 s[16:17], 0

; __device__ __forceinline__ unsigned xb_ld(unsigned* p)              { return __hip_atomic_load(p, __ATOMIC_RELAXED, __HIP_MEMORY_SCOPE_AGENT); }
; #define XB_SPIN(cond, bar) do { unsigned _sp = 0; while (cond) { __builtin_amdgcn_s_sleep(1); \
;     if ((++_sp & 255u) == 0u) { if (xb_ld(&(bar)[XB_TMO])) break; if (_sp > XB_SPIN_CAP) { atomicAdd(&(bar)[XB_TMO], 1u); break; } } } } while (0)
; __device__ __forceinline__ void xcd_barrier(const XcdBarrier& b) {
;     ...
;             XB_SPIN(xb_ld(&bar[XB_XGEN(b.x)]) == gen, bar);
.LBB0_972:
	s_and_b32 s25, s19, 0xff
	s_mov_b64 s[16:17], -1
	s_cmp_lg_u32 s25, 0
	s_mov_b64 s[34:35], -1
	s_sleep 8
	s_cbranch_scc1 .LBB0_975
	global_load_dword v2, v0, s[26:27] offset:512 sc1
	s_waitcnt vmcnt(0)
	v_cmp_eq_u32_e32 vcc, 0, v2
	s_cbranch_vccnz .LBB0_977
	s_mov_b64 s[34:35], 0
	s_mov_b64 s[30:31], -1

; __device__ __forceinline__ unsigned xb_ld(unsigned* p)              { return __hip_atomic_load(p, __ATOMIC_RELAXED, __HIP_MEMORY_SCOPE_AGENT); }
; #define XB_SPIN(cond, bar) do { unsigned _sp = 0; while (cond) { __builtin_amdgcn_s_sleep(1); \
;     if ((++_sp & 255u) == 0u) { if (xb_ld(&(bar)[XB_TMO])) break; if (_sp > XB_SPIN_CAP) { atomicAdd(&(bar)[XB_TMO], 1u); break; } } } } while (0)
; __device__ __forceinline__ void xcd_barrier(const XcdBarrier& b) {
;     ...
;             else XB_SPIN(xb_ld(&bar[XB_TOPGEN]) == tg, bar);
.LBB0_989:
	s_and_b32 s25, s19, 0xff
	s_cmp_lg_u32 s25, 0
	s_mov_b64 s[30:31], -1
	s_sleep 8
	s_cbranch_scc1 .LBB0_992
	global_load_dword v1, v0, s[10:11] sc1
	s_waitcnt vmcnt(0)
	v_cmp_eq_u32_e32 vcc, 0, v1
	s_cbranch_vccnz .LBB0_994
	s_mov_b64 s[30:31], 0
	s_mov_b64 s[26:27], -1
